# residual-GEMM tail unit epilogue: 14 serialized global loads (row stats, residual, column constants) issued up front behind one wait; on v33
# speedup vs baseline: 1.0035x; 1.0035x over previous
.LBB0_925:
	v_add_u32_e32 v1, 0x800, v103
	s_nop 3
	ds_write2_b32 v103, v16, v32 offset1:32
	ds_write2_b32 v103, v17, v33 offset0:64 offset1:96
	ds_write2_b32 v103, v18, v34 offset0:128 offset1:160
	ds_write2_b32 v103, v19, v35 offset0:192 offset1:224
	ds_write2_b32 v1, v20, v36 offset1:32
	ds_write2_b32 v1, v21, v37 offset0:64 offset1:96
	ds_write2_b32 v1, v22, v38 offset0:128 offset1:160
	ds_write2_b32 v1, v23, v39 offset0:192 offset1:224
	v_add_u32_e32 v1, 0x1000, v103
	ds_write2_b32 v1, v24, v40 offset1:32
	ds_write2_b32 v1, v25, v41 offset0:64 offset1:96
	ds_write2_b32 v1, v26, v42 offset0:128 offset1:160
	ds_write2_b32 v1, v27, v43 offset0:192 offset1:224
	v_add_u32_e32 v1, 0x1800, v103
	ds_write2_b32 v1, v28, v44 offset1:32
	ds_write2_b32 v1, v29, v45 offset0:64 offset1:96
	ds_write2_b32 v1, v30, v46 offset0:128 offset1:160
	ds_write2_b32 v1, v31, v47 offset0:192 offset1:224
	s_waitcnt lgkmcnt(0)
	s_barrier
	ds_read2_b64 v[2:5], v105 offset1:16
	s_lshl_b32 s3, s15, 6
	s_lshl_b32 s4, s15, 5
	s_and_b32 s4, s4, 0x60
	s_and_b32 s3, s3, 0xffffff00
	s_waitcnt lgkmcnt(0)
	v_add_f32_e32 v1, 0, v2
	v_add_u32_e32 v2, 0x2000, v105
	v_add_f32_e32 v6, 0, v3
	v_add_f32_e32 v7, 0, v4
	v_add_f32_e32 v8, 0, v5
	ds_read2_b64 v[2:5], v2 offset1:16
	s_or_b32 s3, s3, s4
	v_or_b32_e32 v24, s3, v104
	v_ashrrev_i32_e32 v25, 31, v24
	v_lshl_add_u64 v[110:111], v[24:25], 1, v[86:87]
	v_lshlrev_b64 v[112:113], 2, v[24:25]
	v_lshl_add_u64 v[114:115], s[8:9], 0, v[112:113]
	v_lshl_add_u64 v[112:113], s[6:7], 0, v[112:113]
	global_load_dwordx4 v[116:119], v[84:85], off
	global_load_dwordx4 v[120:123], v[84:85], off offset:16
	global_load_dwordx4 v[124:127], v[84:85], off offset:32
	global_load_dwordx4 v[128:131], v[84:85], off offset:48
	global_load_dwordx4 v[132:135], v[84:85], off offset:64
	global_load_dwordx4 v[136:139], v[84:85], off offset:80
	global_load_dwordx4 v[140:143], v[84:85], off offset:96
	global_load_dwordx4 v[144:147], v[84:85], off offset:112
	global_load_dword v148, v[110:111], off
	global_load_dwordx2 v[150:151], v[112:113], off
	global_load_dwordx2 v[152:153], v[114:115], off
	global_load_dword v149, v[110:111], off offset:256
	global_load_dwordx2 v[154:155], v[112:113], off offset:512
	global_load_dwordx2 v[156:157], v[114:115], off offset:512
	s_mov_b32 s4, s59
	s_waitcnt lgkmcnt(0)
	v_add_f32_e32 v1, v1, v2
	v_add_u32_e32 v2, 0x4000, v105
	v_add_f32_e32 v6, v6, v3
	v_add_f32_e32 v7, v7, v4
	v_add_f32_e32 v8, v8, v5
	ds_read2_b64 v[2:5], v2 offset1:16
	s_waitcnt lgkmcnt(0)
	v_add_f32_e32 v1, v1, v2
	v_add_u32_e32 v2, 0x6000, v105
	v_add_f32_e32 v6, v6, v3
	v_add_f32_e32 v7, v7, v4
	v_add_f32_e32 v8, v8, v5
	ds_read2_b64 v[2:5], v2 offset1:16
	s_waitcnt lgkmcnt(0)
	v_add_f32_e32 v1, v1, v2
	v_add_u32_e32 v2, 0x8000, v105
	v_add_f32_e32 v6, v6, v3
	v_add_f32_e32 v7, v7, v4
	v_add_f32_e32 v8, v8, v5
	ds_read2_b64 v[2:5], v2 offset1:16
	s_waitcnt lgkmcnt(0)
	v_add_f32_e32 v1, v1, v2
	v_add_u32_e32 v2, 0xa000, v105
	v_add_f32_e32 v6, v6, v3
	v_add_f32_e32 v7, v7, v4
	v_add_f32_e32 v8, v8, v5
	ds_read2_b64 v[2:5], v2 offset1:16
	s_waitcnt lgkmcnt(0)
	v_add_f32_e32 v1, v1, v2
	v_add_f32_e32 v2, v7, v4
	v_add_u32_e32 v4, 0xc000, v105
	v_add_f32_e32 v26, v6, v3
	v_add_f32_e32 v3, v8, v5
	ds_read2_b64 v[6:9], v4 offset1:16
	s_waitcnt lgkmcnt(0)
	v_add_f32_e32 v8, v2, v8
	v_add_u32_e32 v2, 0xe000, v105
	v_add_f32_e32 v1, v1, v6
	v_add_f32_e32 v6, v3, v9
	ds_read2_b64 v[2:5], v2 offset1:16
	s_waitcnt lgkmcnt(0)
	v_add_f32_e32 v2, v1, v2
	v_add_f32_e32 v1, v8, v4
	s_waitcnt vmcnt(0)
	v_mov_b64_e32 v[20:21], v[116:117]
	v_mov_b64_e32 v[22:23], v[118:119]
	v_mov_b64_e32 v[16:17], v[120:121]
	v_mov_b64_e32 v[18:19], v[122:123]
	v_mov_b64_e32 v[12:13], v[124:125]
	v_mov_b64_e32 v[14:15], v[126:127]
	v_mov_b64_e32 v[8:9], v[128:129]
	v_mov_b64_e32 v[10:11], v[130:131]
	v_mov_b64_e32 v[28:29], v[132:133]
	v_mov_b64_e32 v[30:31], v[134:135]
	v_mov_b64_e32 v[32:33], v[136:137]
	v_mov_b64_e32 v[34:35], v[138:139]
	s_waitcnt vmcnt(0) lgkmcnt(0)
	v_pk_add_f32 v[20:21], v[20:21], v[22:23]
	s_nop 0
	v_pk_add_f32 v[20:21], v[20:21], 0 op_sel_hi:[1,0]
	v_pk_add_f32 v[16:17], v[16:17], v[18:19]
	v_pk_add_f32 v[12:13], v[12:13], v[14:15]
	v_add_f32_e32 v37, v29, v31
	v_mov_b32_e32 v29, v32
	v_mov_b32_e32 v31, v34
	v_pk_add_f32 v[38:39], v[28:29], v[30:31]
	v_add_f32_e32 v41, v33, v35
	v_mov_b64_e32 v[28:29], v[140:141]
	v_mov_b64_e32 v[30:31], v[142:143]
	v_mov_b64_e32 v[32:33], v[144:145]
	v_mov_b64_e32 v[34:35], v[146:147]
	v_pk_add_f32 v[16:17], v[20:21], v[16:17]
	v_pk_add_f32 v[8:9], v[8:9], v[10:11]
	v_pk_add_f32 v[12:13], v[16:17], v[12:13]
	v_mov_b32_e32 v36, v38
	v_pk_add_f32 v[8:9], v[12:13], v[8:9]
	v_mov_b32_e32 v40, v39
	v_pk_add_f32 v[8:9], v[8:9], v[36:37]
	v_lshl_add_u64 v[10:11], v[24:25], 1, v[86:87]
	v_pk_add_f32 v[8:9], v[8:9], v[40:41]
	s_waitcnt vmcnt(0) lgkmcnt(0)
	v_add_f32_e32 v43, v29, v31
	v_mov_b32_e32 v29, v32
	v_mov_b32_e32 v31, v34
	v_pk_add_f32 v[28:29], v[28:29], v[30:31]
	v_add_f32_e32 v31, v33, v35
	v_mov_b32_e32 v42, v28
	v_pk_add_f32 v[8:9], v[8:9], v[42:43]
	v_mov_b32_e32 v30, v29
	v_pk_add_f32 v[8:9], v[8:9], v[30:31]
	s_nop 0
	v_pk_mul_f32 v[8:9], v[8:9], s[64:65] op_sel_hi:[1,0]
	s_nop 0
	v_fma_f32 v4, -v8, v8, v9
	v_max_f32_e32 v4, 0, v4
	v_add_f32_e32 v4, 0x3727c5ac, v4
	v_cmp_gt_f32_e32 vcc, s35, v4
	v_mul_f32_e32 v9, 0x4b800000, v4
	s_nop 0
	v_cndmask_b32_e32 v4, v4, v9, vcc
	v_rsq_f32_e32 v4, v4
	s_nop 0
	v_mul_f32_e32 v9, 0x45800000, v4
	v_cndmask_b32_e32 v4, v4, v9, vcc
	v_mov_b32_e32 v9, v148
	s_waitcnt vmcnt(0) lgkmcnt(0)
	v_lshlrev_b32_e32 v12, 16, v9
	v_sub_f32_e32 v12, v12, v8
	v_mul_f32_e32 v20, v12, v4
	v_lshlrev_b64 v[12:13], 2, v[24:25]
	v_lshl_add_u64 v[18:19], s[6:7], 0, v[12:13]
	v_lshl_add_u64 v[22:23], s[8:9], 0, v[12:13]
	v_mov_b64_e32 v[14:15], v[150:151]
	v_mov_b64_e32 v[16:17], v[152:153]
	s_waitcnt vmcnt(0) lgkmcnt(0)
	v_fma_f32 v12, v14, v20, v16
	v_mul_f32_e32 v14, v162, v2
	v_and_b32_e32 v2, 0xffff0000, v9
	v_sub_f32_e32 v2, v2, v8
	v_mul_f32_e32 v2, v2, v4
	v_add_f32_e32 v20, v26, v7
	v_mul_f32_e32 v21, v2, v15
	v_mov_b32_e32 v16, v3
	v_pk_add_f32 v[2:3], v[20:21], v[16:17]
	s_nop 0
	v_mul_f32_e32 v16, 0x3fb504f3, v3
	v_pk_fma_f32 v[2:3], v[90:91], v[2:3], v[16:17] op_sel_hi:[1,1,0]
	s_nop 0
	v_pk_mul_f32 v[16:17], v[2:3], v[2:3]
	v_mov_b32_e32 v3, v149
	v_mov_b64_e32 v[20:21], v[154:155]
	s_nop 0
	v_mov_b64_e32 v[18:19], v[156:157]
	s_waitcnt vmcnt(0) lgkmcnt(0)
	v_mov_b32_e32 v187, v21
	v_lshlrev_b32_e32 v7, 16, v3
	v_sub_f32_e32 v7, v7, v8
	v_mul_f32_e32 v7, v7, v4
	v_fma_f32 v7, v20, v7, v18
	v_mul_f32_e32 v9, 0x3fb504f3, v7
	v_mul_f32_e32 v7, v162, v1
	v_and_b32_e32 v1, 0xffff0000, v3
	v_sub_f32_e32 v1, v1, v8
	v_mul_f32_e32 v13, v4, v1
	v_mov_b32_e32 v15, v19
	v_pk_fma_f32 v[12:13], v[186:187], v[12:13], v[14:15]
	v_mov_b32_e32 v8, v5
	v_pk_add_f32 v[4:5], v[6:7], v[8:9]
	v_pk_add_f32 v[6:7], v[12:13], s[4:5]
	s_mov_b32 s5, s70
	v_pk_fma_f32 v[14:15], v[12:13], v[12:13], v[16:17]
	v_pk_mul_f32 v[8:9], v[12:13], s[4:5]
	v_mov_b32_e32 v163, v5
	v_mov_b32_e32 v7, v9
	v_pk_mov_b32 v[8:9], v[8:9], v[14:15] op_sel:[1,0]
	v_pk_mul_f32 v[16:17], v[162:163], v[4:5]
	v_pk_fma_f32 v[8:9], v[162:163], v[4:5], v[8:9]
	v_mov_b32_e32 v3, v16
	v_pk_mov_b32 v[4:5], v[4:5], v[8:9] op_sel:[1,0]
	v_cvt_pk_bf16_f32 v1, v12, v2
	v_pk_add_f32 v[6:7], v[2:3], v[6:7]
	global_store_dword v[10:11], v1, off
	v_cvt_pk_bf16_f32 v1, v4, v5
	v_pk_add_f32 v[14:15], v[4:5], v[6:7]
	v_pk_mul_f32 v[6:7], v[4:5], v[6:7]
	global_store_dword v[10:11], v1, off offset:256
	v_mbcnt_lo_u32_b32 v1, -1, 0
	v_mbcnt_hi_u32_b32 v1, -1, v1
	v_mov_b32_e32 v15, v7
	v_lshlrev_b32_e32 v1, 2, v1
	v_pk_add_f32 v[6:7], v[8:9], v[14:15]
	v_xor_b32_e32 v3, 4, v1
	ds_bpermute_b32 v2, v3, v6
	ds_bpermute_b32 v3, v3, v7
	v_xor_b32_e32 v5, 8, v1
	s_waitcnt lgkmcnt(0)
	v_pk_add_f32 v[2:3], v[6:7], v[2:3]
	ds_bpermute_b32 v4, v5, v2
	ds_bpermute_b32 v5, v5, v3
	s_waitcnt lgkmcnt(0)
	v_pk_add_f32 v[2:3], v[2:3], v[4:5]
	v_xor_b32_e32 v5, 16, v1
	ds_bpermute_b32 v4, v5, v2
	ds_bpermute_b32 v5, v5, v3
	v_xor_b32_e32 v1, 32, v1
	s_waitcnt lgkmcnt(0)
	v_pk_add_f32 v[2:3], v[2:3], v[4:5]
	ds_bpermute_b32 v4, v1, v2
	ds_bpermute_b32 v5, v1, v3
	s_and_saveexec_b64 s[4:5], s[0:1]
	s_cbranch_execz .LBB0_910
	s_lshl_b32 s10, s15, 1
	s_ashr_i32 s11, s10, 31
	v_lshl_add_u64 v[6:7], s[10:11], 2, v[88:89]
	s_waitcnt lgkmcnt(0)
	v_pk_add_f32 v[2:3], v[2:3], v[4:5]
	global_store_dwordx2 v[6:7], v[2:3], off
	s_branch .LBB0_910
